# grid barrier: the XCD leader's agent-scope invalidate moved right behind its write-back (under the cross-XCD round trip) instead of between global and XCD release
# baseline (speedup 1.0000x reference)
; __device__ __forceinline__ unsigned xb_add(unsigned* p, unsigned v) { return __hip_atomic_fetch_add(p, v, __ATOMIC_RELAXED, __HIP_MEMORY_SCOPE_AGENT); }
; __device__ __forceinline__ void xcd_barrier(unsigned* bar, volatile LAS unsigned* st, const int tid) {
;     ...
;         if (old + 1u == (gen + 1u) * nloc) {
;             __builtin_amdgcn_fence(__ATOMIC_RELEASE, "agent");
;             asm volatile("s_waitcnt vmcnt(0)" ::: "memory");
;             const unsigned og = xb_add(&bar[XB_TOP], 1u);
;             const unsigned tg = og / nx;
.LBB0_82:
	s_andn2_saveexec_b64 s[22:23], s[22:23]
	s_cbranch_execz .LBB0_102
	s_mov_b64 s[22:23], exec
	buffer_wbl2 sc1
	s_waitcnt vmcnt(0)
	buffer_inv sc1
	v_mbcnt_lo_u32_b32 v1, s22, 0
	v_mbcnt_hi_u32_b32 v1, s23, v1
	v_cmp_eq_u32_e32 vcc, 0, v1
	s_and_saveexec_b64 s[24:25], vcc
	s_cbranch_execz .LBB0_85
	s_bcnt1_i32_b64 s3, s[22:23]
	v_mov_b32_e32 v2, s3
	v_mov_b32_e32 v3, 0x16e03000
	global_atomic_add v2, v3, v2, s[54:55] offset:1024 sc0

; __device__ __forceinline__ unsigned xb_ld(unsigned* p)              { return __hip_atomic_load(p, __ATOMIC_RELAXED, __HIP_MEMORY_SCOPE_AGENT); }
; __device__ __forceinline__ unsigned xb_add(unsigned* p, unsigned v) { return __hip_atomic_fetch_add(p, v, __ATOMIC_RELAXED, __HIP_MEMORY_SCOPE_AGENT); }
; #define XB_SPIN(cond, bar) do { unsigned _sp = 0; while (cond) { __builtin_amdgcn_s_sleep(1); \
;     if ((++_sp & 255u) == 0u) { if (xb_ld(&(bar)[XB_TMO])) break; if (_sp > XB_SPIN_CAP) { atomicAdd(&(bar)[XB_TMO], 1u); break; } } } } while (0)
; __device__ __forceinline__ void xcd_barrier(unsigned* bar, volatile LAS unsigned* st, const int tid) {
;     ...
;             if (og + 1u == (tg + 1u) * nx) xb_add(&bar[XB_TOPGEN], 1u);
;             else XB_SPIN(xb_ld(&bar[XB_TOPGEN]) == tg, bar);
;             __builtin_amdgcn_fence(__ATOMIC_ACQUIRE, "agent");
;             xb_add(&bar[XB_XGEN(x)], 1u);
;             asm volatile("s_waitcnt vmcnt(0)" ::: "memory");
.LBB0_99:
	s_or_b64 exec, exec, s[14:15]
	s_mov_b64 s[14:15], exec
	v_mbcnt_lo_u32_b32 v0, s14, 0
	v_mbcnt_hi_u32_b32 v0, s15, v0
	v_cmp_eq_u32_e32 vcc, 0, v0
	s_waitcnt vmcnt(0) lgkmcnt(0)
	s_and_saveexec_b64 s[22:23], vcc
	s_cbranch_execz .LBB0_101
	s_bcnt1_i32_b64 s3, s[14:15]
	v_mov_b32_e32 v0, s3
	v_mov_b32_e32 v1, 0x2000
	global_atomic_add v1, v0, s[16:17] offset:1024
